# phase 6 GEMM epilogue stores marked nt so they do not displace the K-loop operands in L2
# speedup vs baseline: 1.0161x; 1.0032x over previous
.LBB0_608:
	s_mov_b32 s59, s1
	v_cvt_pk_bf16_f32 v4, v4, v5
	v_cvt_pk_bf16_f32 v5, v6, v7
	v_cvt_pk_bf16_f32 v6, v0, v1
	v_cvt_pk_bf16_f32 v7, v2, v3
	v_lshl_add_u64 v[0:1], v[16:17], 0, s[58:59]
	s_and_b64 vcc, exec, s[4:5]
	s_mov_b32 s0, s50
	s_mov_b32 s6, s52
	s_mov_b64 s[60:61], s[56:57]
	s_mov_b64 s[58:59], s[54:55]
	global_store_dwordx4 v[0:1], v[4:7], off nt
	s_cbranch_vccnz .LBB0_653

.LBB0_623:
	v_cvt_pk_bf16_f32 v124, v124, v125
	v_cvt_pk_bf16_f32 v125, v126, v127
	v_cvt_pk_bf16_f32 v126, v120, v121
	v_cvt_pk_bf16_f32 v127, v122, v123
	s_and_b64 vcc, exec, s[6:7]
	global_store_dwordx4 v[146:147], v[124:127], off nt
	s_cbranch_vccnz .LBB0_625
	s_mov_b32 s100, 0xbfb8aa3b
	v_pk_mul_f32 v[120:121], v[116:117], s[100:101] op_sel_hi:[1,0]
	v_pk_mul_f32 v[122:123], v[118:119], s[100:101] op_sel_hi:[1,0]
	v_pk_mul_f32 v[124:125], v[112:113], s[100:101] op_sel_hi:[1,0]
	v_pk_mul_f32 v[126:127], v[114:115], s[100:101] op_sel_hi:[1,0]
	v_exp_f32_e32 v120, v120
	v_exp_f32_e32 v121, v121
	v_exp_f32_e32 v122, v122
	v_exp_f32_e32 v123, v123
	v_exp_f32_e32 v124, v124
	v_exp_f32_e32 v125, v125
	v_exp_f32_e32 v126, v126
	v_exp_f32_e32 v127, v127
	v_pk_add_f32 v[120:121], v[120:121], 1.0 op_sel_hi:[1,0]
	v_pk_add_f32 v[122:123], v[122:123], 1.0 op_sel_hi:[1,0]
	v_pk_add_f32 v[124:125], v[124:125], 1.0 op_sel_hi:[1,0]
	v_pk_add_f32 v[126:127], v[126:127], 1.0 op_sel_hi:[1,0]
	v_rcp_f32_e32 v120, v120
	v_rcp_f32_e32 v121, v121
	v_rcp_f32_e32 v122, v122
	v_rcp_f32_e32 v123, v123
	v_rcp_f32_e32 v124, v124
	v_rcp_f32_e32 v126, v126
	v_rcp_f32_e32 v127, v127
	v_rcp_f32_e32 v125, v125
	v_pk_mul_f32 v[118:119], v[118:119], v[122:123]
	v_pk_mul_f32 v[116:117], v[116:117], v[120:121]
	v_pk_mul_f32 v[114:115], v[114:115], v[126:127]
	v_pk_mul_f32 v[112:113], v[112:113], v[124:125]
.LBB0_625:
	s_lshl_b32 s58, s58, 1
	s_mov_b32 s59, s1
	v_cvt_pk_bf16_f32 v116, v116, v117
	v_cvt_pk_bf16_f32 v117, v118, v119
	v_cvt_pk_bf16_f32 v118, v112, v113
	v_cvt_pk_bf16_f32 v119, v114, v115
	v_lshl_add_u64 v[112:113], v[146:147], 0, s[58:59]
	s_and_b64 vcc, exec, s[6:7]
	global_store_dwordx4 v[112:113], v[116:119], off nt
	s_cbranch_vccnz .LBB0_627
	s_mov_b32 s100, 0xbfb8aa3b
	v_pk_mul_f32 v[112:113], v[108:109], s[100:101] op_sel_hi:[1,0]
	v_pk_mul_f32 v[114:115], v[110:111], s[100:101] op_sel_hi:[1,0]
	v_pk_mul_f32 v[116:117], v[104:105], s[100:101] op_sel_hi:[1,0]
	v_pk_mul_f32 v[118:119], v[106:107], s[100:101] op_sel_hi:[1,0]
	v_exp_f32_e32 v112, v112
	v_exp_f32_e32 v113, v113
	v_exp_f32_e32 v114, v114
	v_exp_f32_e32 v115, v115
	v_exp_f32_e32 v116, v116
	v_exp_f32_e32 v117, v117
	v_exp_f32_e32 v118, v118
	v_exp_f32_e32 v119, v119
	v_pk_add_f32 v[112:113], v[112:113], 1.0 op_sel_hi:[1,0]
	v_pk_add_f32 v[114:115], v[114:115], 1.0 op_sel_hi:[1,0]
	v_pk_add_f32 v[116:117], v[116:117], 1.0 op_sel_hi:[1,0]
	v_pk_add_f32 v[118:119], v[118:119], 1.0 op_sel_hi:[1,0]
	v_rcp_f32_e32 v112, v112
	v_rcp_f32_e32 v113, v113
	v_rcp_f32_e32 v114, v114
	v_rcp_f32_e32 v115, v115
	v_rcp_f32_e32 v116, v116
	v_rcp_f32_e32 v118, v118
	v_rcp_f32_e32 v119, v119
	v_rcp_f32_e32 v117, v117
	v_pk_mul_f32 v[110:111], v[110:111], v[114:115]
	v_pk_mul_f32 v[108:109], v[108:109], v[112:113]
	v_pk_mul_f32 v[106:107], v[106:107], v[118:119]
	v_pk_mul_f32 v[104:105], v[104:105], v[116:117]
.LBB0_627:
	s_lshl_b32 s0, s60, 5
	v_lshl_add_u64 v[112:113], v[146:147], 0, s[0:1]
	v_cvt_pk_bf16_f32 v108, v108, v109
	v_cvt_pk_bf16_f32 v109, v110, v111
	v_cvt_pk_bf16_f32 v110, v104, v105
	v_cvt_pk_bf16_f32 v111, v106, v107
	s_and_b64 vcc, exec, s[6:7]
	global_store_dwordx4 v[112:113], v[108:111], off nt
	s_cbranch_vccnz .LBB0_629
	s_mov_b32 s100, 0xbfb8aa3b
	v_pk_mul_f32 v[104:105], v[100:101], s[100:101] op_sel_hi:[1,0]
	v_pk_mul_f32 v[106:107], v[102:103], s[100:101] op_sel_hi:[1,0]
	v_pk_mul_f32 v[108:109], v[96:97], s[100:101] op_sel_hi:[1,0]
	v_pk_mul_f32 v[110:111], v[98:99], s[100:101] op_sel_hi:[1,0]
	v_exp_f32_e32 v104, v104
	v_exp_f32_e32 v105, v105
	v_exp_f32_e32 v106, v106
	v_exp_f32_e32 v107, v107
	v_exp_f32_e32 v108, v108
	v_exp_f32_e32 v109, v109
	v_exp_f32_e32 v110, v110
	v_exp_f32_e32 v111, v111
	v_pk_add_f32 v[104:105], v[104:105], 1.0 op_sel_hi:[1,0]
	v_pk_add_f32 v[106:107], v[106:107], 1.0 op_sel_hi:[1,0]
	v_pk_add_f32 v[108:109], v[108:109], 1.0 op_sel_hi:[1,0]
	v_pk_add_f32 v[110:111], v[110:111], 1.0 op_sel_hi:[1,0]
	v_rcp_f32_e32 v104, v104
	v_rcp_f32_e32 v105, v105
	v_rcp_f32_e32 v106, v106
	v_rcp_f32_e32 v107, v107
	v_rcp_f32_e32 v108, v108
	v_rcp_f32_e32 v110, v110
	v_rcp_f32_e32 v111, v111
	v_rcp_f32_e32 v109, v109
	v_pk_mul_f32 v[102:103], v[102:103], v[106:107]
	v_pk_mul_f32 v[100:101], v[100:101], v[104:105]
	v_pk_mul_f32 v[98:99], v[98:99], v[110:111]
	v_pk_mul_f32 v[96:97], v[96:97], v[108:109]
.LBB0_629:
	s_mov_b32 s59, s1
	v_cvt_pk_bf16_f32 v100, v100, v101
	v_cvt_pk_bf16_f32 v101, v102, v103
	v_cvt_pk_bf16_f32 v102, v96, v97
	v_cvt_pk_bf16_f32 v103, v98, v99
	v_lshl_add_u64 v[96:97], v[112:113], 0, s[58:59]
	s_and_b64 vcc, exec, s[6:7]
	global_store_dwordx4 v[96:97], v[100:103], off nt
	s_cbranch_vccnz .LBB0_631
	s_mov_b32 s100, 0xbfb8aa3b
	v_pk_mul_f32 v[96:97], v[92:93], s[100:101] op_sel_hi:[1,0]
	v_pk_mul_f32 v[98:99], v[94:95], s[100:101] op_sel_hi:[1,0]
	v_pk_mul_f32 v[100:101], v[88:89], s[100:101] op_sel_hi:[1,0]
	v_pk_mul_f32 v[102:103], v[90:91], s[100:101] op_sel_hi:[1,0]
	v_exp_f32_e32 v96, v96
	v_exp_f32_e32 v97, v97
	v_exp_f32_e32 v98, v98
	v_exp_f32_e32 v99, v99
	v_exp_f32_e32 v100, v100
	v_exp_f32_e32 v101, v101
	v_exp_f32_e32 v102, v102
	v_exp_f32_e32 v103, v103
	v_pk_add_f32 v[96:97], v[96:97], 1.0 op_sel_hi:[1,0]
	v_pk_add_f32 v[98:99], v[98:99], 1.0 op_sel_hi:[1,0]
	v_pk_add_f32 v[100:101], v[100:101], 1.0 op_sel_hi:[1,0]
	v_pk_add_f32 v[102:103], v[102:103], 1.0 op_sel_hi:[1,0]
	v_rcp_f32_e32 v96, v96
	v_rcp_f32_e32 v97, v97
	v_rcp_f32_e32 v98, v98
	v_rcp_f32_e32 v99, v99
	v_rcp_f32_e32 v100, v100
	v_rcp_f32_e32 v102, v102
	v_rcp_f32_e32 v103, v103
	v_rcp_f32_e32 v101, v101
	v_pk_mul_f32 v[94:95], v[94:95], v[98:99]
	v_pk_mul_f32 v[92:93], v[92:93], v[96:97]
	v_pk_mul_f32 v[90:91], v[90:91], v[102:103]
	v_pk_mul_f32 v[88:89], v[88:89], v[100:101]
.LBB0_631:
	v_lshl_add_u64 v[96:97], v[112:113], 0, s[0:1]
	v_cvt_pk_bf16_f32 v92, v92, v93
	v_cvt_pk_bf16_f32 v93, v94, v95
	v_cvt_pk_bf16_f32 v94, v88, v89
	v_cvt_pk_bf16_f32 v95, v90, v91
	s_and_b64 vcc, exec, s[6:7]
	global_store_dwordx4 v[96:97], v[92:95], off nt
	s_cbranch_vccnz .LBB0_633
	s_mov_b32 s100, 0xbfb8aa3b
	v_pk_mul_f32 v[88:89], v[84:85], s[100:101] op_sel_hi:[1,0]
	v_pk_mul_f32 v[90:91], v[86:87], s[100:101] op_sel_hi:[1,0]
	v_pk_mul_f32 v[92:93], v[80:81], s[100:101] op_sel_hi:[1,0]
	v_pk_mul_f32 v[94:95], v[82:83], s[100:101] op_sel_hi:[1,0]
	v_exp_f32_e32 v88, v88
	v_exp_f32_e32 v89, v89
	v_exp_f32_e32 v90, v90
	v_exp_f32_e32 v91, v91
	v_exp_f32_e32 v92, v92
	v_exp_f32_e32 v93, v93
	v_exp_f32_e32 v94, v94
	v_exp_f32_e32 v95, v95
	v_pk_add_f32 v[88:89], v[88:89], 1.0 op_sel_hi:[1,0]
	v_pk_add_f32 v[90:91], v[90:91], 1.0 op_sel_hi:[1,0]
	v_pk_add_f32 v[92:93], v[92:93], 1.0 op_sel_hi:[1,0]
	v_pk_add_f32 v[94:95], v[94:95], 1.0 op_sel_hi:[1,0]
	v_rcp_f32_e32 v88, v88
	v_rcp_f32_e32 v89, v89
	v_rcp_f32_e32 v90, v90
	v_rcp_f32_e32 v91, v91
	v_rcp_f32_e32 v92, v92
	v_rcp_f32_e32 v94, v94
	v_rcp_f32_e32 v95, v95
	v_rcp_f32_e32 v93, v93
	v_pk_mul_f32 v[86:87], v[86:87], v[90:91]
	v_pk_mul_f32 v[84:85], v[84:85], v[88:89]
	v_pk_mul_f32 v[82:83], v[82:83], v[94:95]
	v_pk_mul_f32 v[80:81], v[80:81], v[92:93]
.LBB0_633:
	s_mov_b32 s59, s1
	v_cvt_pk_bf16_f32 v84, v84, v85
	v_cvt_pk_bf16_f32 v85, v86, v87
	v_cvt_pk_bf16_f32 v86, v80, v81
	v_cvt_pk_bf16_f32 v87, v82, v83
	v_lshl_add_u64 v[80:81], v[96:97], 0, s[58:59]
	s_and_b64 vcc, exec, s[6:7]
	global_store_dwordx4 v[80:81], v[84:87], off nt
	s_cbranch_vccnz .LBB0_635
	s_mov_b32 s100, 0xbfb8aa3b
	v_pk_mul_f32 v[80:81], v[76:77], s[100:101] op_sel_hi:[1,0]
	v_pk_mul_f32 v[82:83], v[78:79], s[100:101] op_sel_hi:[1,0]
	v_pk_mul_f32 v[84:85], v[72:73], s[100:101] op_sel_hi:[1,0]
	v_pk_mul_f32 v[86:87], v[74:75], s[100:101] op_sel_hi:[1,0]
	v_exp_f32_e32 v80, v80
	v_exp_f32_e32 v81, v81
	v_exp_f32_e32 v82, v82
	v_exp_f32_e32 v83, v83
	v_exp_f32_e32 v84, v84
	v_exp_f32_e32 v85, v85
	v_exp_f32_e32 v86, v86
	v_exp_f32_e32 v87, v87
	v_pk_add_f32 v[80:81], v[80:81], 1.0 op_sel_hi:[1,0]
	v_pk_add_f32 v[82:83], v[82:83], 1.0 op_sel_hi:[1,0]
	v_pk_add_f32 v[84:85], v[84:85], 1.0 op_sel_hi:[1,0]
	v_pk_add_f32 v[86:87], v[86:87], 1.0 op_sel_hi:[1,0]
	v_rcp_f32_e32 v80, v80
	v_rcp_f32_e32 v81, v81
	v_rcp_f32_e32 v82, v82
	v_rcp_f32_e32 v83, v83
	v_rcp_f32_e32 v84, v84
	v_rcp_f32_e32 v86, v86
	v_rcp_f32_e32 v87, v87
	v_rcp_f32_e32 v85, v85
	v_pk_mul_f32 v[78:79], v[78:79], v[82:83]
	v_pk_mul_f32 v[76:77], v[76:77], v[80:81]
	v_pk_mul_f32 v[74:75], v[74:75], v[86:87]
	v_pk_mul_f32 v[72:73], v[72:73], v[84:85]
.LBB0_635:
	v_lshl_add_u64 v[80:81], v[96:97], 0, s[0:1]
	v_cvt_pk_bf16_f32 v76, v76, v77
	v_cvt_pk_bf16_f32 v77, v78, v79
	v_cvt_pk_bf16_f32 v78, v72, v73
	v_cvt_pk_bf16_f32 v79, v74, v75
	s_and_b64 vcc, exec, s[6:7]
	global_store_dwordx4 v[80:81], v[76:79], off nt
	s_cbranch_vccnz .LBB0_637
	s_mov_b32 s100, 0xbfb8aa3b
	v_pk_mul_f32 v[72:73], v[68:69], s[100:101] op_sel_hi:[1,0]
	v_pk_mul_f32 v[74:75], v[70:71], s[100:101] op_sel_hi:[1,0]
	v_pk_mul_f32 v[76:77], v[64:65], s[100:101] op_sel_hi:[1,0]
	v_pk_mul_f32 v[78:79], v[66:67], s[100:101] op_sel_hi:[1,0]
	v_exp_f32_e32 v72, v72
	v_exp_f32_e32 v73, v73
	v_exp_f32_e32 v74, v74
	v_exp_f32_e32 v75, v75
	v_exp_f32_e32 v76, v76
	v_exp_f32_e32 v77, v77
	v_exp_f32_e32 v78, v78
	v_exp_f32_e32 v79, v79
	v_pk_add_f32 v[72:73], v[72:73], 1.0 op_sel_hi:[1,0]
	v_pk_add_f32 v[74:75], v[74:75], 1.0 op_sel_hi:[1,0]
	v_pk_add_f32 v[76:77], v[76:77], 1.0 op_sel_hi:[1,0]
	v_pk_add_f32 v[78:79], v[78:79], 1.0 op_sel_hi:[1,0]
	v_rcp_f32_e32 v72, v72
	v_rcp_f32_e32 v73, v73
	v_rcp_f32_e32 v74, v74
	v_rcp_f32_e32 v75, v75
	v_rcp_f32_e32 v76, v76
	v_rcp_f32_e32 v78, v78
	v_rcp_f32_e32 v79, v79
	v_rcp_f32_e32 v77, v77
	v_pk_mul_f32 v[70:71], v[70:71], v[74:75]
	v_pk_mul_f32 v[68:69], v[68:69], v[72:73]
	v_pk_mul_f32 v[66:67], v[66:67], v[78:79]
	v_pk_mul_f32 v[64:65], v[64:65], v[76:77]
.LBB0_637:
	s_mov_b32 s59, s1
	v_cvt_pk_bf16_f32 v68, v68, v69
	v_cvt_pk_bf16_f32 v69, v70, v71
	v_cvt_pk_bf16_f32 v70, v64, v65
	v_cvt_pk_bf16_f32 v71, v66, v67
	v_lshl_add_u64 v[64:65], v[80:81], 0, s[58:59]
	s_and_b64 vcc, exec, s[6:7]
	global_store_dwordx4 v[64:65], v[68:71], off nt
	s_cbranch_vccnz .LBB0_639
	s_mov_b32 s100, 0xbfb8aa3b
	v_pk_mul_f32 v[64:65], v[60:61], s[100:101] op_sel_hi:[1,0]
	v_pk_mul_f32 v[66:67], v[62:63], s[100:101] op_sel_hi:[1,0]
	v_pk_mul_f32 v[68:69], v[56:57], s[100:101] op_sel_hi:[1,0]
	v_pk_mul_f32 v[70:71], v[58:59], s[100:101] op_sel_hi:[1,0]
	v_exp_f32_e32 v64, v64
	v_exp_f32_e32 v65, v65
	v_exp_f32_e32 v66, v66
	v_exp_f32_e32 v67, v67
	v_exp_f32_e32 v68, v68
	v_exp_f32_e32 v69, v69
	v_exp_f32_e32 v70, v70
	v_exp_f32_e32 v71, v71
	v_pk_add_f32 v[64:65], v[64:65], 1.0 op_sel_hi:[1,0]
	v_pk_add_f32 v[66:67], v[66:67], 1.0 op_sel_hi:[1,0]
	v_pk_add_f32 v[68:69], v[68:69], 1.0 op_sel_hi:[1,0]
	v_pk_add_f32 v[70:71], v[70:71], 1.0 op_sel_hi:[1,0]
	v_rcp_f32_e32 v64, v64
	v_rcp_f32_e32 v65, v65
	v_rcp_f32_e32 v66, v66
	v_rcp_f32_e32 v67, v67
	v_rcp_f32_e32 v68, v68
	v_rcp_f32_e32 v70, v70
	v_rcp_f32_e32 v71, v71
	v_rcp_f32_e32 v69, v69
	v_pk_mul_f32 v[62:63], v[62:63], v[66:67]
	v_pk_mul_f32 v[60:61], v[60:61], v[64:65]
	v_pk_mul_f32 v[58:59], v[58:59], v[70:71]
	v_pk_mul_f32 v[56:57], v[56:57], v[68:69]
.LBB0_639:
	s_mulk_i32 s60, 0xa0
	s_mov_b32 s61, s1
	v_lshl_add_u64 v[64:65], v[80:81], 0, s[60:61]
	v_cvt_pk_bf16_f32 v60, v60, v61
	v_cvt_pk_bf16_f32 v61, v62, v63
	v_cvt_pk_bf16_f32 v62, v56, v57
	v_cvt_pk_bf16_f32 v63, v58, v59
	s_and_b64 vcc, exec, s[6:7]
	global_store_dwordx4 v[64:65], v[60:63], off nt
	s_cbranch_vccnz .LBB0_641
	s_mov_b32 s100, 0xbfb8aa3b
	v_pk_mul_f32 v[56:57], v[52:53], s[100:101] op_sel_hi:[1,0]
	v_pk_mul_f32 v[58:59], v[54:55], s[100:101] op_sel_hi:[1,0]
	v_pk_mul_f32 v[60:61], v[48:49], s[100:101] op_sel_hi:[1,0]
	v_pk_mul_f32 v[62:63], v[50:51], s[100:101] op_sel_hi:[1,0]
	v_exp_f32_e32 v56, v56
	v_exp_f32_e32 v57, v57
	v_exp_f32_e32 v58, v58
	v_exp_f32_e32 v59, v59
	v_exp_f32_e32 v60, v60
	v_exp_f32_e32 v61, v61
	v_exp_f32_e32 v62, v62
	v_exp_f32_e32 v63, v63
	v_pk_add_f32 v[56:57], v[56:57], 1.0 op_sel_hi:[1,0]
	v_pk_add_f32 v[58:59], v[58:59], 1.0 op_sel_hi:[1,0]
	v_pk_add_f32 v[60:61], v[60:61], 1.0 op_sel_hi:[1,0]
	v_pk_add_f32 v[62:63], v[62:63], 1.0 op_sel_hi:[1,0]
	v_rcp_f32_e32 v56, v56
	v_rcp_f32_e32 v57, v57
	v_rcp_f32_e32 v58, v58
	v_rcp_f32_e32 v59, v59
	v_rcp_f32_e32 v60, v60
	v_rcp_f32_e32 v62, v62
	v_rcp_f32_e32 v63, v63
	v_rcp_f32_e32 v61, v61
	v_pk_mul_f32 v[54:55], v[54:55], v[58:59]
	v_pk_mul_f32 v[52:53], v[52:53], v[56:57]
	v_pk_mul_f32 v[50:51], v[50:51], v[62:63]
	v_pk_mul_f32 v[48:49], v[48:49], v[60:61]
.LBB0_641:
	s_mov_b32 s59, s1
	v_cvt_pk_bf16_f32 v52, v52, v53
	v_cvt_pk_bf16_f32 v53, v54, v55
	v_cvt_pk_bf16_f32 v54, v48, v49
	v_cvt_pk_bf16_f32 v55, v50, v51
	v_lshl_add_u64 v[48:49], v[64:65], 0, s[58:59]
	s_and_b64 vcc, exec, s[6:7]
	global_store_dwordx4 v[48:49], v[52:55], off nt
	s_cbranch_vccnz .LBB0_643
	s_mov_b32 s100, 0xbfb8aa3b
	v_pk_mul_f32 v[48:49], v[44:45], s[100:101] op_sel_hi:[1,0]
	v_pk_mul_f32 v[50:51], v[46:47], s[100:101] op_sel_hi:[1,0]
	v_pk_mul_f32 v[52:53], v[40:41], s[100:101] op_sel_hi:[1,0]
	v_pk_mul_f32 v[54:55], v[42:43], s[100:101] op_sel_hi:[1,0]
	v_exp_f32_e32 v48, v48
	v_exp_f32_e32 v49, v49
	v_exp_f32_e32 v50, v50
	v_exp_f32_e32 v51, v51
	v_exp_f32_e32 v52, v52
	v_exp_f32_e32 v53, v53
	v_exp_f32_e32 v54, v54
	v_exp_f32_e32 v55, v55
	v_pk_add_f32 v[48:49], v[48:49], 1.0 op_sel_hi:[1,0]
	v_pk_add_f32 v[50:51], v[50:51], 1.0 op_sel_hi:[1,0]
	v_pk_add_f32 v[52:53], v[52:53], 1.0 op_sel_hi:[1,0]
	v_pk_add_f32 v[54:55], v[54:55], 1.0 op_sel_hi:[1,0]
	v_rcp_f32_e32 v48, v48
	v_rcp_f32_e32 v49, v49
	v_rcp_f32_e32 v50, v50
	v_rcp_f32_e32 v51, v51
	v_rcp_f32_e32 v52, v52
	v_rcp_f32_e32 v54, v54
	v_rcp_f32_e32 v55, v55
	v_rcp_f32_e32 v53, v53
	v_pk_mul_f32 v[46:47], v[46:47], v[50:51]
	v_pk_mul_f32 v[44:45], v[44:45], v[48:49]
	v_pk_mul_f32 v[42:43], v[42:43], v[54:55]
	v_pk_mul_f32 v[40:41], v[40:41], v[52:53]
.LBB0_643:
	v_lshl_add_u64 v[48:49], v[64:65], 0, s[0:1]
	v_cvt_pk_bf16_f32 v44, v44, v45
	v_cvt_pk_bf16_f32 v45, v46, v47
	v_cvt_pk_bf16_f32 v46, v40, v41
	v_cvt_pk_bf16_f32 v47, v42, v43
	s_and_b64 vcc, exec, s[6:7]
	global_store_dwordx4 v[48:49], v[44:47], off nt
	s_cbranch_vccnz .LBB0_645
	s_mov_b32 s100, 0xbfb8aa3b
	v_pk_mul_f32 v[40:41], v[36:37], s[100:101] op_sel_hi:[1,0]
	v_pk_mul_f32 v[42:43], v[38:39], s[100:101] op_sel_hi:[1,0]
	v_pk_mul_f32 v[44:45], v[32:33], s[100:101] op_sel_hi:[1,0]
	v_pk_mul_f32 v[46:47], v[34:35], s[100:101] op_sel_hi:[1,0]
	v_exp_f32_e32 v40, v40
	v_exp_f32_e32 v41, v41
	v_exp_f32_e32 v42, v42
	v_exp_f32_e32 v43, v43
	v_exp_f32_e32 v44, v44
	v_exp_f32_e32 v45, v45
	v_exp_f32_e32 v46, v46
	v_exp_f32_e32 v47, v47
	v_pk_add_f32 v[40:41], v[40:41], 1.0 op_sel_hi:[1,0]
	v_pk_add_f32 v[42:43], v[42:43], 1.0 op_sel_hi:[1,0]
	v_pk_add_f32 v[44:45], v[44:45], 1.0 op_sel_hi:[1,0]
	v_pk_add_f32 v[46:47], v[46:47], 1.0 op_sel_hi:[1,0]
	v_rcp_f32_e32 v40, v40
	v_rcp_f32_e32 v41, v41
	v_rcp_f32_e32 v42, v42
	v_rcp_f32_e32 v43, v43
	v_rcp_f32_e32 v44, v44
	v_rcp_f32_e32 v46, v46
	v_rcp_f32_e32 v47, v47
	v_rcp_f32_e32 v45, v45
	v_pk_mul_f32 v[38:39], v[38:39], v[42:43]
	v_pk_mul_f32 v[36:37], v[36:37], v[40:41]
	v_pk_mul_f32 v[34:35], v[34:35], v[46:47]
	v_pk_mul_f32 v[32:33], v[32:33], v[44:45]
.LBB0_645:
	s_mov_b32 s59, s1
	v_cvt_pk_bf16_f32 v36, v36, v37
	v_cvt_pk_bf16_f32 v37, v38, v39
	v_cvt_pk_bf16_f32 v38, v32, v33
	v_cvt_pk_bf16_f32 v39, v34, v35
	v_lshl_add_u64 v[32:33], v[48:49], 0, s[58:59]
	s_and_b64 vcc, exec, s[6:7]
	global_store_dwordx4 v[32:33], v[36:39], off nt
	s_cbranch_vccnz .LBB0_647
	s_mov_b32 s100, 0xbfb8aa3b
	v_pk_mul_f32 v[32:33], v[28:29], s[100:101] op_sel_hi:[1,0]
	v_pk_mul_f32 v[34:35], v[30:31], s[100:101] op_sel_hi:[1,0]
	v_pk_mul_f32 v[36:37], v[24:25], s[100:101] op_sel_hi:[1,0]
	v_pk_mul_f32 v[38:39], v[26:27], s[100:101] op_sel_hi:[1,0]
	v_exp_f32_e32 v32, v32
	v_exp_f32_e32 v33, v33
	v_exp_f32_e32 v34, v34
	v_exp_f32_e32 v35, v35
	v_exp_f32_e32 v36, v36
	v_exp_f32_e32 v37, v37
	v_exp_f32_e32 v38, v38
	v_exp_f32_e32 v39, v39
	v_pk_add_f32 v[32:33], v[32:33], 1.0 op_sel_hi:[1,0]
	v_pk_add_f32 v[34:35], v[34:35], 1.0 op_sel_hi:[1,0]
	v_pk_add_f32 v[36:37], v[36:37], 1.0 op_sel_hi:[1,0]
	v_pk_add_f32 v[38:39], v[38:39], 1.0 op_sel_hi:[1,0]
	v_rcp_f32_e32 v32, v32
	v_rcp_f32_e32 v33, v33
	v_rcp_f32_e32 v34, v34
	v_rcp_f32_e32 v35, v35
	v_rcp_f32_e32 v36, v36
	v_rcp_f32_e32 v38, v38
	v_rcp_f32_e32 v39, v39
	v_rcp_f32_e32 v37, v37
	v_pk_mul_f32 v[30:31], v[30:31], v[34:35]
	v_pk_mul_f32 v[28:29], v[28:29], v[32:33]
	v_pk_mul_f32 v[26:27], v[26:27], v[38:39]
	v_pk_mul_f32 v[24:25], v[24:25], v[36:37]
.LBB0_647:
	v_lshl_add_u64 v[32:33], v[48:49], 0, s[0:1]
	v_cvt_pk_bf16_f32 v28, v28, v29
	v_cvt_pk_bf16_f32 v29, v30, v31
	v_cvt_pk_bf16_f32 v30, v24, v25
	v_cvt_pk_bf16_f32 v31, v26, v27
	s_and_b64 vcc, exec, s[6:7]
	global_store_dwordx4 v[32:33], v[28:31], off nt
	s_cbranch_vccnz .LBB0_649
	s_mov_b32 s100, 0xbfb8aa3b
	v_pk_mul_f32 v[24:25], v[20:21], s[100:101] op_sel_hi:[1,0]
	v_pk_mul_f32 v[26:27], v[22:23], s[100:101] op_sel_hi:[1,0]
	v_pk_mul_f32 v[28:29], v[16:17], s[100:101] op_sel_hi:[1,0]
	v_pk_mul_f32 v[30:31], v[18:19], s[100:101] op_sel_hi:[1,0]
	v_exp_f32_e32 v24, v24
	v_exp_f32_e32 v25, v25
	v_exp_f32_e32 v26, v26
	v_exp_f32_e32 v27, v27
	v_exp_f32_e32 v28, v28
	v_exp_f32_e32 v29, v29
	v_exp_f32_e32 v30, v30
	v_exp_f32_e32 v31, v31
	v_pk_add_f32 v[24:25], v[24:25], 1.0 op_sel_hi:[1,0]
	v_pk_add_f32 v[26:27], v[26:27], 1.0 op_sel_hi:[1,0]
	v_pk_add_f32 v[28:29], v[28:29], 1.0 op_sel_hi:[1,0]
	v_pk_add_f32 v[30:31], v[30:31], 1.0 op_sel_hi:[1,0]
	v_rcp_f32_e32 v24, v24
	v_rcp_f32_e32 v25, v25
	v_rcp_f32_e32 v26, v26
	v_rcp_f32_e32 v27, v27
	v_rcp_f32_e32 v28, v28
	v_rcp_f32_e32 v30, v30
	v_rcp_f32_e32 v31, v31
	v_rcp_f32_e32 v29, v29
	v_pk_mul_f32 v[22:23], v[22:23], v[26:27]
	v_pk_mul_f32 v[20:21], v[20:21], v[24:25]
	v_pk_mul_f32 v[18:19], v[18:19], v[30:31]
	v_pk_mul_f32 v[16:17], v[16:17], v[28:29]
.LBB0_649:
	s_mov_b32 s59, s1
	v_cvt_pk_bf16_f32 v20, v20, v21
	v_cvt_pk_bf16_f32 v21, v22, v23
	v_cvt_pk_bf16_f32 v22, v16, v17
	v_cvt_pk_bf16_f32 v23, v18, v19
	v_lshl_add_u64 v[16:17], v[32:33], 0, s[58:59]
	s_and_b64 vcc, exec, s[6:7]
	global_store_dwordx4 v[16:17], v[20:23], off nt
	s_cbranch_vccnz .LBB0_651
	s_mov_b32 s100, 0xbfb8aa3b
	v_pk_mul_f32 v[16:17], v[12:13], s[100:101] op_sel_hi:[1,0]
	v_pk_mul_f32 v[18:19], v[14:15], s[100:101] op_sel_hi:[1,0]
	v_pk_mul_f32 v[20:21], v[8:9], s[100:101] op_sel_hi:[1,0]
	v_pk_mul_f32 v[22:23], v[10:11], s[100:101] op_sel_hi:[1,0]
	v_exp_f32_e32 v16, v16
	v_exp_f32_e32 v17, v17
	v_exp_f32_e32 v18, v18
	v_exp_f32_e32 v19, v19
	v_exp_f32_e32 v20, v20
	v_exp_f32_e32 v21, v21
	v_exp_f32_e32 v22, v22
	v_exp_f32_e32 v23, v23
	v_pk_add_f32 v[16:17], v[16:17], 1.0 op_sel_hi:[1,0]
	v_pk_add_f32 v[18:19], v[18:19], 1.0 op_sel_hi:[1,0]
	v_pk_add_f32 v[20:21], v[20:21], 1.0 op_sel_hi:[1,0]
	v_pk_add_f32 v[22:23], v[22:23], 1.0 op_sel_hi:[1,0]
	v_rcp_f32_e32 v16, v16
	v_rcp_f32_e32 v17, v17
	v_rcp_f32_e32 v18, v18
	v_rcp_f32_e32 v19, v19
	v_rcp_f32_e32 v20, v20
	v_rcp_f32_e32 v22, v22
	v_rcp_f32_e32 v23, v23
	v_rcp_f32_e32 v21, v21
	v_pk_mul_f32 v[14:15], v[14:15], v[18:19]
	v_pk_mul_f32 v[12:13], v[12:13], v[16:17]
	v_pk_mul_f32 v[10:11], v[10:11], v[22:23]
	v_pk_mul_f32 v[8:9], v[8:9], v[20:21]
.LBB0_651:
	v_lshl_add_u64 v[16:17], v[32:33], 0, s[0:1]
	v_cvt_pk_bf16_f32 v12, v12, v13
	v_cvt_pk_bf16_f32 v13, v14, v15
	v_cvt_pk_bf16_f32 v14, v8, v9
	v_cvt_pk_bf16_f32 v15, v10, v11
	s_and_b64 vcc, exec, s[6:7]
	global_store_dwordx4 v[16:17], v[12:15], off nt
	s_cbranch_vccnz .LBB0_608
	s_mov_b32 s100, 0xbfb8aa3b
	v_pk_mul_f32 v[8:9], v[4:5], s[100:101] op_sel_hi:[1,0]
	v_pk_mul_f32 v[10:11], v[6:7], s[100:101] op_sel_hi:[1,0]
	v_pk_mul_f32 v[12:13], v[0:1], s[100:101] op_sel_hi:[1,0]
	v_pk_mul_f32 v[14:15], v[2:3], s[100:101] op_sel_hi:[1,0]
	v_exp_f32_e32 v8, v8
	v_exp_f32_e32 v9, v9
	v_exp_f32_e32 v10, v10
	v_exp_f32_e32 v11, v11
	v_exp_f32_e32 v12, v12
	v_exp_f32_e32 v13, v13
	v_exp_f32_e32 v14, v14
	v_exp_f32_e32 v15, v15
	v_pk_add_f32 v[8:9], v[8:9], 1.0 op_sel_hi:[1,0]
	v_pk_add_f32 v[10:11], v[10:11], 1.0 op_sel_hi:[1,0]
	v_pk_add_f32 v[12:13], v[12:13], 1.0 op_sel_hi:[1,0]
	v_pk_add_f32 v[14:15], v[14:15], 1.0 op_sel_hi:[1,0]
	v_rcp_f32_e32 v8, v8
	v_rcp_f32_e32 v9, v9
	v_rcp_f32_e32 v10, v10
	v_rcp_f32_e32 v11, v11
	v_rcp_f32_e32 v12, v12
	v_rcp_f32_e32 v14, v14
	v_rcp_f32_e32 v15, v15
	v_rcp_f32_e32 v13, v13
	v_pk_mul_f32 v[6:7], v[6:7], v[10:11]
	v_pk_mul_f32 v[4:5], v[4:5], v[8:9]
	v_pk_mul_f32 v[2:3], v[2:3], v[14:15]
	v_pk_mul_f32 v[0:1], v[0:1], v[12:13]
	s_branch .LBB0_608
